# hand-written FFN-in swiglu epilogue: packed f32 math, 4 element pairs interleaved per stage (no hazard nops), saddr stores; on top of norm2+final
# speedup vs baseline: 1.0014x; 1.0003x over previous
.LBB0_348:
	v_lshl_add_u32 v156, s24, 8, v140
	v_lshl_or_b32 v155, s25, 7, v142
	v_mul_u32_u24_e32 v154, 0x1600, v156
	v_lshl_add_u32 v154, v155, 1, v154
	v_mov_b32_e32 v158, 0xbfb8aa3b
	v_mov_b32_e32 v159, 0xbfb8aa3b
	v_pk_mul_f32 v[160:161], v[124:125], v[158:159]
	v_pk_mul_f32 v[162:163], v[126:127], v[158:159]
	v_pk_mul_f32 v[164:165], v[116:117], v[158:159]
	v_pk_mul_f32 v[168:169], v[118:119], v[158:159]
	v_exp_f32_e32 v160, v160
	v_exp_f32_e32 v161, v161
	v_exp_f32_e32 v162, v162
	v_exp_f32_e32 v163, v163
	v_exp_f32_e32 v164, v164
	v_exp_f32_e32 v165, v165
	v_exp_f32_e32 v168, v168
	v_exp_f32_e32 v169, v169
	v_pk_add_f32 v[160:161], v[160:161], 1.0 op_sel_hi:[1,0]
	v_pk_add_f32 v[162:163], v[162:163], 1.0 op_sel_hi:[1,0]
	v_pk_add_f32 v[164:165], v[164:165], 1.0 op_sel_hi:[1,0]
	v_pk_add_f32 v[168:169], v[168:169], 1.0 op_sel_hi:[1,0]
	v_rcp_f32_e32 v160, v160
	v_rcp_f32_e32 v161, v161
	v_rcp_f32_e32 v162, v162
	v_rcp_f32_e32 v163, v163
	v_rcp_f32_e32 v164, v164
	v_rcp_f32_e32 v165, v165
	v_rcp_f32_e32 v168, v168
	v_rcp_f32_e32 v169, v169
	v_pk_mul_f32 v[160:161], v[124:125], v[160:161]
	v_pk_mul_f32 v[162:163], v[126:127], v[162:163]
	v_pk_mul_f32 v[164:165], v[116:117], v[164:165]
	v_pk_mul_f32 v[168:169], v[118:119], v[168:169]
	v_pk_mul_f32 v[160:161], v[160:161], v[120:121]
	v_pk_mul_f32 v[162:163], v[162:163], v[122:123]
	v_pk_mul_f32 v[164:165], v[164:165], v[112:113]
	v_pk_mul_f32 v[168:169], v[168:169], v[114:115]
	v_cvt_pk_bf16_f32 v170, v160, v161
	v_cvt_pk_bf16_f32 v171, v162, v163
	v_cvt_pk_bf16_f32 v172, v164, v165
	v_cvt_pk_bf16_f32 v173, v168, v169
	global_store_dwordx4 v154, v[170:173], s[12:13] sc1
	v_pk_mul_f32 v[160:161], v[108:109], v[158:159]
	v_pk_mul_f32 v[162:163], v[110:111], v[158:159]
	v_pk_mul_f32 v[164:165], v[100:101], v[158:159]
	v_pk_mul_f32 v[168:169], v[102:103], v[158:159]
	v_exp_f32_e32 v160, v160
	v_exp_f32_e32 v161, v161
	v_exp_f32_e32 v162, v162
	v_exp_f32_e32 v163, v163
	v_exp_f32_e32 v164, v164
	v_exp_f32_e32 v165, v165
	v_exp_f32_e32 v168, v168
	v_exp_f32_e32 v169, v169
	v_pk_add_f32 v[160:161], v[160:161], 1.0 op_sel_hi:[1,0]
	v_pk_add_f32 v[162:163], v[162:163], 1.0 op_sel_hi:[1,0]
	v_pk_add_f32 v[164:165], v[164:165], 1.0 op_sel_hi:[1,0]
	v_pk_add_f32 v[168:169], v[168:169], 1.0 op_sel_hi:[1,0]
	v_rcp_f32_e32 v160, v160
	v_rcp_f32_e32 v161, v161
	v_rcp_f32_e32 v162, v162
	v_rcp_f32_e32 v163, v163
	v_rcp_f32_e32 v164, v164
	v_rcp_f32_e32 v165, v165
	v_rcp_f32_e32 v168, v168
	v_rcp_f32_e32 v169, v169
	v_pk_mul_f32 v[160:161], v[108:109], v[160:161]
	v_pk_mul_f32 v[162:163], v[110:111], v[162:163]
	v_pk_mul_f32 v[164:165], v[100:101], v[164:165]
	v_pk_mul_f32 v[168:169], v[102:103], v[168:169]
	v_pk_mul_f32 v[160:161], v[160:161], v[104:105]
	v_pk_mul_f32 v[162:163], v[162:163], v[106:107]
	v_pk_mul_f32 v[164:165], v[164:165], v[96:97]
	v_pk_mul_f32 v[168:169], v[168:169], v[98:99]
	v_add_u32_e32 v155, 0x16000, v154
	v_cvt_pk_bf16_f32 v170, v160, v161
	v_cvt_pk_bf16_f32 v171, v162, v163
	v_cvt_pk_bf16_f32 v172, v164, v165
	v_cvt_pk_bf16_f32 v173, v168, v169
	global_store_dwordx4 v155, v[170:173], s[12:13] sc1
	v_pk_mul_f32 v[160:161], v[92:93], v[158:159]
	v_pk_mul_f32 v[162:163], v[94:95], v[158:159]
	v_pk_mul_f32 v[164:165], v[84:85], v[158:159]
	v_pk_mul_f32 v[168:169], v[86:87], v[158:159]
	v_exp_f32_e32 v160, v160
	v_exp_f32_e32 v161, v161
	v_exp_f32_e32 v162, v162
	v_exp_f32_e32 v163, v163
	v_exp_f32_e32 v164, v164
	v_exp_f32_e32 v165, v165
	v_exp_f32_e32 v168, v168
	v_exp_f32_e32 v169, v169
	v_pk_add_f32 v[160:161], v[160:161], 1.0 op_sel_hi:[1,0]
	v_pk_add_f32 v[162:163], v[162:163], 1.0 op_sel_hi:[1,0]
	v_pk_add_f32 v[164:165], v[164:165], 1.0 op_sel_hi:[1,0]
	v_pk_add_f32 v[168:169], v[168:169], 1.0 op_sel_hi:[1,0]
	v_rcp_f32_e32 v160, v160
	v_rcp_f32_e32 v161, v161
	v_rcp_f32_e32 v162, v162
	v_rcp_f32_e32 v163, v163
	v_rcp_f32_e32 v164, v164
	v_rcp_f32_e32 v165, v165
	v_rcp_f32_e32 v168, v168
	v_rcp_f32_e32 v169, v169
	v_pk_mul_f32 v[160:161], v[92:93], v[160:161]
	v_pk_mul_f32 v[162:163], v[94:95], v[162:163]
	v_pk_mul_f32 v[164:165], v[84:85], v[164:165]
	v_pk_mul_f32 v[168:169], v[86:87], v[168:169]
	v_pk_mul_f32 v[160:161], v[160:161], v[88:89]
	v_pk_mul_f32 v[162:163], v[162:163], v[90:91]
	v_pk_mul_f32 v[164:165], v[164:165], v[80:81]
	v_pk_mul_f32 v[168:169], v[168:169], v[82:83]
	v_add_u32_e32 v155, 0x2c000, v154
	v_cvt_pk_bf16_f32 v170, v160, v161
	v_cvt_pk_bf16_f32 v171, v162, v163
	v_cvt_pk_bf16_f32 v172, v164, v165
	v_cvt_pk_bf16_f32 v173, v168, v169
	global_store_dwordx4 v155, v[170:173], s[12:13] sc1
	v_pk_mul_f32 v[160:161], v[76:77], v[158:159]
	v_pk_mul_f32 v[162:163], v[78:79], v[158:159]
	v_pk_mul_f32 v[164:165], v[68:69], v[158:159]
	v_pk_mul_f32 v[168:169], v[70:71], v[158:159]
	v_exp_f32_e32 v160, v160
	v_exp_f32_e32 v161, v161
	v_exp_f32_e32 v162, v162
	v_exp_f32_e32 v163, v163
	v_exp_f32_e32 v164, v164
	v_exp_f32_e32 v165, v165
	v_exp_f32_e32 v168, v168
	v_exp_f32_e32 v169, v169
	v_pk_add_f32 v[160:161], v[160:161], 1.0 op_sel_hi:[1,0]
	v_pk_add_f32 v[162:163], v[162:163], 1.0 op_sel_hi:[1,0]
	v_pk_add_f32 v[164:165], v[164:165], 1.0 op_sel_hi:[1,0]
	v_pk_add_f32 v[168:169], v[168:169], 1.0 op_sel_hi:[1,0]
	v_rcp_f32_e32 v160, v160
	v_rcp_f32_e32 v161, v161
	v_rcp_f32_e32 v162, v162
	v_rcp_f32_e32 v163, v163
	v_rcp_f32_e32 v164, v164
	v_rcp_f32_e32 v165, v165
	v_rcp_f32_e32 v168, v168
	v_rcp_f32_e32 v169, v169
	v_pk_mul_f32 v[160:161], v[76:77], v[160:161]
	v_pk_mul_f32 v[162:163], v[78:79], v[162:163]
	v_pk_mul_f32 v[164:165], v[68:69], v[164:165]
	v_pk_mul_f32 v[168:169], v[70:71], v[168:169]
	v_pk_mul_f32 v[160:161], v[160:161], v[72:73]
	v_pk_mul_f32 v[162:163], v[162:163], v[74:75]
	v_pk_mul_f32 v[164:165], v[164:165], v[64:65]
	v_pk_mul_f32 v[168:169], v[168:169], v[66:67]
	v_add_u32_e32 v155, 0x42000, v154
	v_cvt_pk_bf16_f32 v170, v160, v161
	v_cvt_pk_bf16_f32 v171, v162, v163
	v_cvt_pk_bf16_f32 v172, v164, v165
	v_cvt_pk_bf16_f32 v173, v168, v169
	global_store_dwordx4 v155, v[170:173], s[12:13] sc1
	v_pk_mul_f32 v[160:161], v[60:61], v[158:159]
	v_pk_mul_f32 v[162:163], v[62:63], v[158:159]
	v_pk_mul_f32 v[164:165], v[52:53], v[158:159]
	v_pk_mul_f32 v[168:169], v[54:55], v[158:159]
	v_exp_f32_e32 v160, v160
	v_exp_f32_e32 v161, v161
	v_exp_f32_e32 v162, v162
	v_exp_f32_e32 v163, v163
	v_exp_f32_e32 v164, v164
	v_exp_f32_e32 v165, v165
	v_exp_f32_e32 v168, v168
	v_exp_f32_e32 v169, v169
	v_pk_add_f32 v[160:161], v[160:161], 1.0 op_sel_hi:[1,0]
	v_pk_add_f32 v[162:163], v[162:163], 1.0 op_sel_hi:[1,0]
	v_pk_add_f32 v[164:165], v[164:165], 1.0 op_sel_hi:[1,0]
	v_pk_add_f32 v[168:169], v[168:169], 1.0 op_sel_hi:[1,0]
	v_rcp_f32_e32 v160, v160
	v_rcp_f32_e32 v161, v161
	v_rcp_f32_e32 v162, v162
	v_rcp_f32_e32 v163, v163
	v_rcp_f32_e32 v164, v164
	v_rcp_f32_e32 v165, v165
	v_rcp_f32_e32 v168, v168
	v_rcp_f32_e32 v169, v169
	v_pk_mul_f32 v[160:161], v[60:61], v[160:161]
	v_pk_mul_f32 v[162:163], v[62:63], v[162:163]
	v_pk_mul_f32 v[164:165], v[52:53], v[164:165]
	v_pk_mul_f32 v[168:169], v[54:55], v[168:169]
	v_pk_mul_f32 v[160:161], v[160:161], v[56:57]
	v_pk_mul_f32 v[162:163], v[162:163], v[58:59]
	v_pk_mul_f32 v[164:165], v[164:165], v[48:49]
	v_pk_mul_f32 v[168:169], v[168:169], v[50:51]
	v_add_u32_e32 v155, 0xb0000, v154
	v_cvt_pk_bf16_f32 v170, v160, v161
	v_cvt_pk_bf16_f32 v171, v162, v163
	v_cvt_pk_bf16_f32 v172, v164, v165
	v_cvt_pk_bf16_f32 v173, v168, v169
	global_store_dwordx4 v155, v[170:173], s[12:13] sc1
	v_pk_mul_f32 v[160:161], v[44:45], v[158:159]
	v_pk_mul_f32 v[162:163], v[46:47], v[158:159]
	v_pk_mul_f32 v[164:165], v[36:37], v[158:159]
	v_pk_mul_f32 v[168:169], v[38:39], v[158:159]
	v_exp_f32_e32 v160, v160
	v_exp_f32_e32 v161, v161
	v_exp_f32_e32 v162, v162
	v_exp_f32_e32 v163, v163
	v_exp_f32_e32 v164, v164
	v_exp_f32_e32 v165, v165
	v_exp_f32_e32 v168, v168
	v_exp_f32_e32 v169, v169
	v_pk_add_f32 v[160:161], v[160:161], 1.0 op_sel_hi:[1,0]
	v_pk_add_f32 v[162:163], v[162:163], 1.0 op_sel_hi:[1,0]
	v_pk_add_f32 v[164:165], v[164:165], 1.0 op_sel_hi:[1,0]
	v_pk_add_f32 v[168:169], v[168:169], 1.0 op_sel_hi:[1,0]
	v_rcp_f32_e32 v160, v160
	v_rcp_f32_e32 v161, v161
	v_rcp_f32_e32 v162, v162
	v_rcp_f32_e32 v163, v163
	v_rcp_f32_e32 v164, v164
	v_rcp_f32_e32 v165, v165
	v_rcp_f32_e32 v168, v168
	v_rcp_f32_e32 v169, v169
	v_pk_mul_f32 v[160:161], v[44:45], v[160:161]
	v_pk_mul_f32 v[162:163], v[46:47], v[162:163]
	v_pk_mul_f32 v[164:165], v[36:37], v[164:165]
	v_pk_mul_f32 v[168:169], v[38:39], v[168:169]
	v_pk_mul_f32 v[160:161], v[160:161], v[40:41]
	v_pk_mul_f32 v[162:163], v[162:163], v[42:43]
	v_pk_mul_f32 v[164:165], v[164:165], v[32:33]
	v_pk_mul_f32 v[168:169], v[168:169], v[34:35]
	v_add_u32_e32 v155, 0xc6000, v154
	v_cvt_pk_bf16_f32 v170, v160, v161
	v_cvt_pk_bf16_f32 v171, v162, v163
	v_cvt_pk_bf16_f32 v172, v164, v165
	v_cvt_pk_bf16_f32 v173, v168, v169
	global_store_dwordx4 v155, v[170:173], s[12:13] sc1
	v_pk_mul_f32 v[160:161], v[28:29], v[158:159]
	v_pk_mul_f32 v[162:163], v[30:31], v[158:159]
	v_pk_mul_f32 v[164:165], v[20:21], v[158:159]
	v_pk_mul_f32 v[168:169], v[22:23], v[158:159]
	v_exp_f32_e32 v160, v160
	v_exp_f32_e32 v161, v161
	v_exp_f32_e32 v162, v162
	v_exp_f32_e32 v163, v163
	v_exp_f32_e32 v164, v164
	v_exp_f32_e32 v165, v165
	v_exp_f32_e32 v168, v168
	v_exp_f32_e32 v169, v169
	v_pk_add_f32 v[160:161], v[160:161], 1.0 op_sel_hi:[1,0]
	v_pk_add_f32 v[162:163], v[162:163], 1.0 op_sel_hi:[1,0]
	v_pk_add_f32 v[164:165], v[164:165], 1.0 op_sel_hi:[1,0]
	v_pk_add_f32 v[168:169], v[168:169], 1.0 op_sel_hi:[1,0]
	v_rcp_f32_e32 v160, v160
	v_rcp_f32_e32 v161, v161
	v_rcp_f32_e32 v162, v162
	v_rcp_f32_e32 v163, v163
	v_rcp_f32_e32 v164, v164
	v_rcp_f32_e32 v165, v165
	v_rcp_f32_e32 v168, v168
	v_rcp_f32_e32 v169, v169
	v_pk_mul_f32 v[160:161], v[28:29], v[160:161]
	v_pk_mul_f32 v[162:163], v[30:31], v[162:163]
	v_pk_mul_f32 v[164:165], v[20:21], v[164:165]
	v_pk_mul_f32 v[168:169], v[22:23], v[168:169]
	v_pk_mul_f32 v[160:161], v[160:161], v[24:25]
	v_pk_mul_f32 v[162:163], v[162:163], v[26:27]
	v_pk_mul_f32 v[164:165], v[164:165], v[16:17]
	v_pk_mul_f32 v[168:169], v[168:169], v[18:19]
	v_add_u32_e32 v155, 0xdc000, v154
	v_cvt_pk_bf16_f32 v170, v160, v161
	v_cvt_pk_bf16_f32 v171, v162, v163
	v_cvt_pk_bf16_f32 v172, v164, v165
	v_cvt_pk_bf16_f32 v173, v168, v169
	global_store_dwordx4 v155, v[170:173], s[12:13] sc1
	v_pk_mul_f32 v[160:161], v[12:13], v[158:159]
	v_pk_mul_f32 v[162:163], v[14:15], v[158:159]
	v_pk_mul_f32 v[164:165], v[4:5], v[158:159]
	v_pk_mul_f32 v[168:169], v[6:7], v[158:159]
	v_exp_f32_e32 v160, v160
	v_exp_f32_e32 v161, v161
	v_exp_f32_e32 v162, v162
	v_exp_f32_e32 v163, v163
	v_exp_f32_e32 v164, v164
	v_exp_f32_e32 v165, v165
	v_exp_f32_e32 v168, v168
	v_exp_f32_e32 v169, v169
	v_pk_add_f32 v[160:161], v[160:161], 1.0 op_sel_hi:[1,0]
	v_pk_add_f32 v[162:163], v[162:163], 1.0 op_sel_hi:[1,0]
	v_pk_add_f32 v[164:165], v[164:165], 1.0 op_sel_hi:[1,0]
	v_pk_add_f32 v[168:169], v[168:169], 1.0 op_sel_hi:[1,0]
	v_rcp_f32_e32 v160, v160
	v_rcp_f32_e32 v161, v161
	v_rcp_f32_e32 v162, v162
	v_rcp_f32_e32 v163, v163
	v_rcp_f32_e32 v164, v164
	v_rcp_f32_e32 v165, v165
	v_rcp_f32_e32 v168, v168
	v_rcp_f32_e32 v169, v169
	v_pk_mul_f32 v[160:161], v[12:13], v[160:161]
	v_pk_mul_f32 v[162:163], v[14:15], v[162:163]
	v_pk_mul_f32 v[164:165], v[4:5], v[164:165]
	v_pk_mul_f32 v[168:169], v[6:7], v[168:169]
	v_pk_mul_f32 v[160:161], v[160:161], v[8:9]
	v_pk_mul_f32 v[162:163], v[162:163], v[10:11]
	v_pk_mul_f32 v[164:165], v[164:165], v[0:1]
	v_pk_mul_f32 v[168:169], v[168:169], v[2:3]
	v_add_u32_e32 v155, 0xf2000, v154
	v_cvt_pk_bf16_f32 v170, v160, v161
	v_cvt_pk_bf16_f32 v171, v162, v163
	v_cvt_pk_bf16_f32 v172, v164, v165
	v_cvt_pk_bf16_f32 v173, v168, v169
	global_store_dwordx4 v155, v[170:173], s[12:13] sc1
	s_andn2_b64 vcc, exec, s[0:1]
	s_mov_b64 s[24:25], -1
	s_cbranch_vccnz .LBB0_341
	s_andn2_b64 vcc, exec, s[4:5]
	s_cbranch_vccnz .LBB0_340
	s_barrier
	s_branch .LBB0_340
